# W2 weight conversion moved from the prologue into the idle tail workgroups of the SwiGLU GEMM phase (prologue item loop reversed and parametrized)
# speedup vs baseline: 1.0121x; 1.0121x over previous
_Z10fwd_kernel4Args:
	s_mov_b32 s94, s2
	s_load_dwordx8 s[76:83], s[0:1], 0x80
	s_load_dword s2, s[0:1], 0xb8
	s_load_dwordx4 s[84:87], s[0:1], 0xa0
	s_load_dwordx2 s[88:89], s[0:1], 0xb0
	s_add_u32 s58, s0, 0xb0
	v_and_b32_e32 v165, 0x3ff, v0
	s_addc_u32 s59, s1, 0
	v_cmp_gt_u32_e32 vcc, 2, v165
	s_waitcnt lgkmcnt(0)
	v_writelane_b32 v228, s2, 0
	s_mov_b32 s101, 0
	s_mov_b32 s100, 0
	s_movk_i32 s99, 0x44ff
	s_cmp_lg_u32 s88, 0x100
	s_cbranch_scc1 .Lp0_full
	s_movk_i32 s99, 0x39ff
.Lp0_full:
	s_and_saveexec_b64 s[4:5], vcc
	v_lshl_add_u32 v1, v165, 2, 0
	v_add_u32_e32 v1, 0x23fc0, v1
	v_mov_b32_e32 v2, 0
	ds_write_b32 v1, v2
	s_or_b64 exec, exec, s[4:5]
	s_load_dwordx16 s[60:75], s[0:1], 0x0
	s_add_u32 s2, s84, 0x30000
	s_addc_u32 s3, s85, 0
	v_writelane_b32 v228, s2, 1
	s_waitcnt lgkmcnt(0)
	s_barrier
	v_writelane_b32 v228, s3, 2
	s_getreg_b32 s2, hwreg(HW_REG_XCC_ID, 0, 4)
	s_and_b32 s2, s2, 15
	v_writelane_b32 v228, s2, 3
	v_cmp_eq_u32_e64 s[2:3], 0, v165
	s_mov_b64 s[4:5], exec
	s_nop 0
	v_writelane_b32 v228, s2, 4
	s_nop 1
	v_writelane_b32 v228, s3, 5
	s_and_b64 s[2:3], s[4:5], s[2:3]
	s_mov_b64 exec, s[2:3]
	s_cbranch_execz .LBB0_5
	s_mov_b64 s[6:7], exec
	v_mbcnt_lo_u32_b32 v1, s6, 0
	v_mbcnt_hi_u32_b32 v1, s7, v1
	v_cmp_eq_u32_e32 vcc, 0, v1
	s_and_b64 s[2:3], exec, vcc
	s_mov_b64 exec, s[2:3]
	s_cbranch_execz .LBB0_5
	v_readlane_b32 s2, v228, 3
	s_lshl_b32 s2, s2, 8
	s_bcnt1_i32_b64 s3, s[6:7]
	v_mov_b32_e32 v1, s2
	v_mov_b32_e32 v2, s3
	v_readlane_b32 s2, v228, 1
	v_readlane_b32 s3, v228, 2
	s_nop 4
	global_atomic_add v1, v2, s[2:3] offset:1024

.Lp0_entry:
	s_load_dwordx16 s[8:23], s[0:1], 0x40
	s_lshl_b32 s1, s101, 7
	s_sub_i32 s1, s94, s1
	s_lshl_b32 s1, s1, 3
	s_add_u32 s2, s84, 0x7600000
	s_addc_u32 s3, s85, 0
	s_add_u32 s26, s84, 0x4a00000
	s_addc_u32 s27, s85, 0
	s_add_u32 s28, s84, 0x4800000
	s_addc_u32 s29, s85, 0
	s_add_u32 s30, s84, 0x4600000
	s_addc_u32 s31, s85, 0
	s_add_u32 s34, s84, 0x3e00000
	s_addc_u32 s35, s85, 0
	s_add_u32 s36, s84, 0x3800400
	s_addc_u32 s37, s85, 0
	s_add_u32 s38, s84, 0x3800000
	s_addc_u32 s39, s85, 0
	s_add_u32 s40, s84, 0x3400000
	s_addc_u32 s41, s85, 0
	s_add_u32 s42, s84, 0x200000
	v_readfirstlane_b32 s0, v165
	s_addc_u32 s43, s85, 0
	s_lshr_b32 s0, s0, 6
	s_add_i32 s24, s0, s1
	s_mov_b32 s98, s24
	s_sub_i32 s24, s99, s24
	v_bfe_u32 v1, v165, 4, 2
	v_lshlrev_b32_e32 v2, 2, v165
	s_cmpk_lt_i32 s24, 0x4500
	v_writelane_b32 v228, s2, 14
	v_and_b32_e32 v170, 60, v2
	v_or_b32_e32 v171, 4, v1
	v_or_b32_e32 v172, 8, v1
	v_or_b32_e32 v173, 12, v1
	v_or_b32_e32 v174, 16, v1
	v_or_b32_e32 v175, 20, v1
	v_or_b32_e32 v176, 24, v1
	v_or_b32_e32 v177, 28, v1
	v_or_b32_e32 v178, 32, v1
	v_or_b32_e32 v179, 36, v1
	v_or_b32_e32 v180, 40, v1
	v_or_b32_e32 v181, 44, v1
	v_or_b32_e32 v182, 48, v1
	v_or_b32_e32 v183, 52, v1
	v_or_b32_e32 v184, 56, v1
	s_cselect_b64 s[44:45], -1, 0
	s_cmpk_gt_i32 s24, 0x44ff
	v_or_b32_e32 v185, 60, v1
	v_writelane_b32 v228, s3, 15
	s_cbranch_scc1 .LBB0_17
	s_cmpk_gt_i32 s24, 0x18ff
	s_cbranch_scc0 .LBB0_18
	s_cmpk_gt_u32 s24, 0x1aff
	s_cbranch_scc0 .LBB0_19
	s_cmpk_gt_u32 s24, 0x1bff
	s_cbranch_scc0 .LBB0_20
	s_cmpk_gt_u32 s24, 0x1dff
	s_cbranch_scc0 .LBB0_21
	s_cmpk_gt_u32 s24, 0x21ff
	s_cbranch_scc0 .LBB0_22
	s_cmpk_gt_u32 s24, 0x22ff
	s_cbranch_scc0 .LBB0_23
	s_cmpk_gt_u32 s24, 0x23ff
	s_cbranch_scc0 .LBB0_24
	s_cmpk_gt_u32 s24, 0x2eff
	s_cbranch_scc0 .LBB0_25
	s_cmpk_gt_u32 s24, 0x39ff
	s_cbranch_scc0 .LBB0_26
	s_lshl_b32 s1, s24, 6
	s_and_b32 s54, s1, 0x7c0
	s_lshl_b32 s1, s24, 1
	s_and_b32 s1, s1, 0x7fffffc0
	s_add_i32 s48, s1, 0xffff8c00
	s_mov_b64 s[46:47], 0
	s_mov_b64 s[50:51], 0
	s_mov_b64 s[4:5], s[78:79]
	s_branch .LBB0_27

.LBB0_76:
	v_and_b32_e32 v164, 63, v165
	s_andn2_b64 vcc, exec, s[44:45]
	s_lshl_b32 s44, s88, 3
	s_lshr_b32 s44, s44, s101
	s_cbranch_vccnz .LBB0_154
	s_sub_i32 s44, 0, s44
	v_lshlrev_b32_e32 v18, 3, v165
	v_lshrrev_b32_e32 v186, 3, v164
	v_and_b32_e32 v34, 56, v18
	s_mulk_i32 s0, 0x4200
	v_mul_u32_u24_e32 v18, 0x104, v34
	v_mov_b32_e32 v19, 0
	s_add_i32 s0, s0, 0
	v_lshlrev_b32_e32 v20, 2, v186
	v_mul_u32_u24_e32 v35, 0x104, v1
	v_lshl_add_u32 v100, v170, 2, s0
	v_add3_u32 v194, s0, v18, v20
	v_mov_b32_e32 v20, v19
	v_mov_b32_e32 v21, v19
	v_mov_b32_e32 v22, v19
	v_mov_b32_e32 v23, v19
	v_mov_b32_e32 v24, v19
	v_mov_b32_e32 v25, v19
	v_mov_b32_e32 v26, v19
	v_mov_b32_e32 v27, v19
	v_mov_b32_e32 v28, v19
	v_mov_b32_e32 v29, v19
	v_mov_b32_e32 v30, v19
	v_mov_b32_e32 v31, v19
	v_mov_b32_e32 v32, v19
	v_mov_b32_e32 v33, v19
	v_writelane_b32 v228, s94, 16
	s_add_i32 s0, s44, s24
	v_mov_b32_e32 v18, v19
	v_add_u32_e32 v195, v100, v35
	v_lshlrev_b32_e32 v166, 1, v34
	v_mov_b64_e32 v[34:35], v[32:33]
	v_writelane_b32 v228, s95, 17
	v_or_b32_e32 v187, 8, v186
	v_or_b32_e32 v188, 16, v186
	v_or_b32_e32 v189, 24, v186
	v_or_b32_e32 v190, 32, v186
	v_or_b32_e32 v191, 40, v186
	v_or_b32_e32 v192, 48, v186
	v_or_b32_e32 v193, 56, v186
	s_lshl_b32 s25, s0, 6
	s_lshl_b32 s33, s44, 6
	s_lshl_b32 s45, s0, 1
	s_lshl_b32 s88, s44, 1
	s_lshl_b32 s89, s0, 3
	s_lshl_b32 s92, s44, 3
	s_lshl_b32 s93, s0, 2
	s_lshl_b32 s94, s44, 2
	s_mov_b32 s97, 0
	s_mov_b64 s[52:53], 0
	s_mov_b32 s95, 1.0
	s_mov_b32 s96, s24
	v_mov_b64_e32 v[32:33], v[30:31]
	v_mov_b64_e32 v[30:31], v[28:29]
	v_mov_b64_e32 v[28:29], v[26:27]
	v_mov_b64_e32 v[26:27], v[24:25]
	v_mov_b64_e32 v[24:25], v[22:23]
	v_mov_b64_e32 v[22:23], v[20:21]
	v_mov_b64_e32 v[20:21], v[18:19]
	s_mov_b32 s1, 0
	s_mov_b32 s0, 0
	s_branch .LBB0_80

.LBB0_80:
	s_add_i32 s96, s96, s44
	s_cmp_lt_i32 s96, s100
	s_cselect_b64 s[50:51], -1, 0
	s_and_b64 vcc, exec, s[50:51]
	s_cbranch_vccnz .LBB0_79
	s_cmpk_gt_i32 s96, 0x18ff
	s_cbranch_scc0 .LBB0_91
	s_cmpk_gt_u32 s96, 0x1aff
	s_cbranch_scc0 .LBB0_92
	s_cmpk_gt_u32 s96, 0x1bff
	s_cbranch_scc0 .LBB0_93
	s_cmpk_gt_u32 s96, 0x1dff
	s_cbranch_scc0 .LBB0_94
	s_cmpk_gt_u32 s96, 0x21ff
	s_cbranch_scc0 .LBB0_95
	s_cmpk_gt_u32 s96, 0x22ff
	s_cbranch_scc0 .LBB0_96
	s_cmpk_gt_u32 s96, 0x23ff
	s_cbranch_scc0 .LBB0_97
	s_cmpk_gt_u32 s96, 0x2eff
	s_cbranch_scc0 .LBB0_98
	s_cmpk_gt_u32 s96, 0x39ff
	s_cbranch_scc0 .LBB0_99
	s_and_b32 s0, s45, 0x7fffffc0
	s_and_b32 s90, s25, 0x7c0
	s_add_i32 s97, s0, 0xffff8c00
	s_mov_b64 s[52:53], 0
	s_mov_b64 s[54:55], 0
	s_mov_b64 s[4:5], s[78:79]
	s_branch .LBB0_100

.LBB0_154:
	s_cmp_lg_u32 s101, 0
	s_cbranch_scc1 .Ltramp_back
	s_mov_b32 s24, s98
	s_cmpk_gt_i32 s24, 0x23ff
	s_cbranch_scc0 .LBB0_156
	s_branch .LBB0_162
.LBB0_155:
	v_readlane_b32 s88, v228, 6
	v_readlane_b32 s58, v228, 12
	v_readlane_b32 s94, v228, 16
	v_readlane_b32 s89, v228, 7
	v_readlane_b32 s59, v228, 13
	v_readlane_b32 s95, v228, 17
	s_cmp_lg_u32 s101, 0
	s_cbranch_scc1 .Ltramp_back
	s_mov_b32 s24, s98
	s_lshl_b32 s44, s88, 3
	s_cmpk_gt_i32 s24, 0x23ff
	s_cbranch_scc1 .LBB0_162

.LBB0_755:
	s_waitcnt lgkmcnt(0)
	s_barrier
	ds_read_b128 v[96:99], v168 offset:35840
	ds_read_b128 v[100:103], v168 offset:35904
	ds_read_b128 v[104:107], v168 offset:35968
	ds_read_b128 v[108:111], v168 offset:36032
	ds_read_b128 v[90:93], v158 offset:53248
	ds_read_b128 v[182:185], v158 offset:53312
	s_waitcnt lgkmcnt(1)
	v_mfma_f32_16x16x32_bf16 v[90:93], v[90:93], v[96:99], 0
	v_mov_b32_e32 v94, s77
	v_mov_b32_e32 v112, s77
	s_waitcnt lgkmcnt(0)
	v_mfma_f32_16x16x32_bf16 v[90:93], v[182:185], v[100:103], v[90:93]
	ds_read_b128 v[182:185], v158 offset:53376
	s_waitcnt lgkmcnt(0)
	v_mfma_f32_16x16x32_bf16 v[90:93], v[182:185], v[104:107], v[90:93]
	ds_read_b128 v[182:185], v158 offset:53440
	s_waitcnt lgkmcnt(0)
	v_mfma_f32_16x16x32_bf16 v[90:93], v[182:185], v[108:111], v[90:93]
	s_nop 7
	v_cndmask_b32_e64 v94, v90, v94, s[22:23]
	v_cndmask_b32_e64 v90, v94, v90, s[24:25]
	v_cndmask_b32_e64 v91, 0, v91, s[24:25]
	v_cndmask_b32_e64 v92, v92, 0, s[26:27]
	v_cndmask_b32_e64 v93, v93, 0, s[28:29]
	v_cvt_pk_bf16_f32 v90, v90, v91
	v_cvt_pk_bf16_f32 v91, v92, v93
	ds_read_b128 v[92:95], v158 offset:57600
	ds_read_b128 v[182:185], v158 offset:57664
	s_waitcnt lgkmcnt(1)
	v_mfma_f32_16x16x32_bf16 v[92:95], v[92:95], v[96:99], 0
	s_waitcnt lgkmcnt(0)
	v_mfma_f32_16x16x32_bf16 v[92:95], v[182:185], v[100:103], v[92:95]
	ds_read_b128 v[182:185], v158 offset:57728
	s_waitcnt lgkmcnt(0)
	v_mfma_f32_16x16x32_bf16 v[92:95], v[182:185], v[104:107], v[92:95]
	ds_read_b128 v[182:185], v158 offset:57792
	s_waitcnt lgkmcnt(0)
	v_mfma_f32_16x16x32_bf16 v[92:95], v[182:185], v[108:111], v[92:95]
	s_nop 7
	v_cndmask_b32_e64 v92, v92, v112, s[30:31]
	v_cndmask_b32_e64 v93, v93, 0, s[34:35]
	v_cndmask_b32_e64 v94, v94, 0, s[36:37]
	v_cndmask_b32_e64 v95, v95, 0, s[38:39]
	v_cvt_pk_bf16_f32 v92, v92, v93
	v_cvt_pk_bf16_f32 v93, v94, v95
	ds_read_b128 v[182:185], v158 offset:61952
	ds_read_b128 v[186:189], v158 offset:62016
	s_waitcnt lgkmcnt(1)
	v_mfma_f32_16x16x32_bf16 v[182:185], v[182:185], v[96:99], 0
	v_mov_b32_e32 v94, s77
	s_waitcnt lgkmcnt(0)
	v_mfma_f32_16x16x32_bf16 v[182:185], v[186:189], v[100:103], v[182:185]
	ds_read_b128 v[186:189], v158 offset:62080
	s_waitcnt lgkmcnt(0)
	v_mfma_f32_16x16x32_bf16 v[182:185], v[186:189], v[104:107], v[182:185]
	ds_read_b128 v[186:189], v158 offset:62144
	s_waitcnt lgkmcnt(0)
	v_mfma_f32_16x16x32_bf16 v[182:185], v[186:189], v[108:111], v[182:185]
	s_nop 7
	v_cndmask_b32_e64 v94, v182, v94, s[40:41]
	v_cndmask_b32_e64 v95, v183, 0, s[42:43]
	v_cndmask_b32_e64 v112, v184, 0, s[44:45]
	v_cndmask_b32_e64 v113, v185, 0, s[46:47]
	v_cvt_pk_bf16_f32 v94, v94, v95
	v_cvt_pk_bf16_f32 v95, v112, v113
	ds_read_b128 v[182:185], v159 offset:13056
	s_waitcnt lgkmcnt(0)
	v_mfma_f32_16x16x32_bf16 v[96:99], v[182:185], v[96:99], 0
	ds_read_b128 v[182:185], v159 offset:13120
	s_waitcnt lgkmcnt(0)
	v_mfma_f32_16x16x32_bf16 v[96:99], v[182:185], v[100:103], v[96:99]
	ds_read_b128 v[100:103], v159 offset:13184
	s_waitcnt lgkmcnt(0)
	v_mfma_f32_16x16x32_bf16 v[96:99], v[100:103], v[104:107], v[96:99]
	ds_read_b128 v[100:103], v159 offset:13248
	s_waitcnt lgkmcnt(0)
	v_mfma_f32_16x16x32_bf16 v[96:99], v[100:103], v[108:111], v[96:99]
	v_mov_b32_e32 v100, s77
	s_nop 6
	v_cndmask_b32_e64 v96, v96, v100, s[48:49]
	v_cndmask_b32_e64 v97, v97, 0, s[50:51]
	v_cndmask_b32_e64 v98, v98, 0, s[52:53]
	v_cndmask_b32_e64 v99, v99, 0, s[54:55]
	v_cvt_pk_bf16_f32 v96, v96, v97
	v_cvt_pk_bf16_f32 v97, v98, v99
	ds_read_b128 v[110:113], v168 offset:18432
	ds_read_b128 v[98:101], v168 offset:18496
	ds_read_b128 v[102:105], v168 offset:18560
	ds_read_b128 v[106:109], v168 offset:18624
	s_waitcnt vmcnt(5) lgkmcnt(3)
	v_mfma_f32_16x16x32_bf16 v[38:41], v[38:41], v[110:113], 0
	v_mfma_f32_16x16x32_bf16 v[54:57], v[54:57], v[110:113], 0
	v_mfma_f32_16x16x32_bf16 v[58:61], v[58:61], v[110:113], 0
	s_waitcnt vmcnt(4) lgkmcnt(2)
	v_mfma_f32_16x16x32_bf16 v[26:29], v[26:29], v[98:101], v[38:41]
	v_mfma_f32_16x16x32_bf16 v[74:77], v[74:77], v[110:113], 0
	v_mfma_f32_16x16x32_bf16 v[50:53], v[50:53], v[98:101], v[54:57]
	v_mfma_f32_16x16x32_bf16 v[58:61], v[62:65], v[98:101], v[58:61]
	s_waitcnt vmcnt(3) lgkmcnt(1)
	v_mfma_f32_16x16x32_bf16 v[26:29], v[30:33], v[102:105], v[26:29]
	v_mfma_f32_16x16x32_bf16 v[74:77], v[78:81], v[98:101], v[74:77]
	ds_read2_b64 v[78:81], v169 offset1:4
	v_mfma_f32_16x16x32_bf16 v[46:49], v[46:49], v[102:105], v[50:53]
	v_mfma_f32_16x16x32_bf16 v[58:61], v[66:69], v[102:105], v[58:61]
	v_add_u32_e32 v66, 0x800, v169
	ds_read2_b64 v[62:65], v66 offset0:32 offset1:36
	v_add_u32_e32 v50, 0x1000, v169
	s_waitcnt vmcnt(2) lgkmcnt(2)
	v_mfma_f32_16x16x32_bf16 v[26:29], v[34:37], v[106:109], v[26:29]
	v_add_u32_e32 v34, 0x1800, v169
	ds_read2_b64 v[30:33], v34 offset0:96 offset1:100
	v_mfma_f32_16x16x32_bf16 v[74:77], v[82:85], v[102:105], v[74:77]
	v_mfma_f32_16x16x32_bf16 v[42:45], v[42:45], v[106:109], v[46:49]
	s_nop 2
	ds_read2_b64 v[46:49], v50 offset0:64 offset1:68
	v_mfma_f32_16x16x32_bf16 v[74:77], v[86:89], v[106:109], v[74:77]
	v_mfma_f32_16x16x32_bf16 v[58:61], v[70:73], v[106:109], v[58:61]
	s_waitcnt lgkmcnt(3)
	v_mfma_f32_16x16x32_bf16 v[74:77], v[78:81], v[90:93], v[74:77]
	ds_read2_b64 v[78:81], v169 offset0:8 offset1:12
	s_waitcnt lgkmcnt(3)
	v_mfma_f32_16x16x32_bf16 v[58:61], v[62:65], v[90:93], v[58:61]
	ds_read2_b64 v[62:65], v66 offset0:40 offset1:44
	s_waitcnt lgkmcnt(3)
	v_mfma_f32_16x16x32_bf16 v[26:29], v[30:33], v[90:93], v[26:29]
	ds_read2_b64 v[30:33], v34 offset0:104 offset1:108
	s_waitcnt lgkmcnt(3)
	v_mfma_f32_16x16x32_bf16 v[42:45], v[46:49], v[90:93], v[42:45]
	ds_read2_b64 v[46:49], v50 offset0:72 offset1:76
	s_waitcnt lgkmcnt(3)
	v_mfma_f32_16x16x32_bf16 v[74:77], v[78:81], v[94:97], v[74:77]
	s_waitcnt lgkmcnt(2)
	v_mfma_f32_16x16x32_bf16 v[58:61], v[62:65], v[94:97], v[58:61]
	s_waitcnt lgkmcnt(1)
	v_mfma_f32_16x16x32_bf16 v[26:29], v[30:33], v[94:97], v[26:29]
	s_nop 3
	v_mul_f32_e32 v78, v75, v75
	v_mul_f32_e32 v79, v77, v77
	v_mul_f32_e32 v62, v59, v59
	s_waitcnt lgkmcnt(0)
	v_mfma_f32_16x16x32_bf16 v[42:45], v[46:49], v[94:97], v[42:45]
	v_mul_f32_e32 v63, v61, v61
	v_mul_f32_e32 v30, v27, v27
	v_mul_f32_e32 v31, v29, v29
	v_fmac_f32_e32 v78, v74, v74
	v_fmac_f32_e32 v79, v76, v76
	v_fmac_f32_e32 v62, v58, v58
	v_fmac_f32_e32 v63, v60, v60
	s_nop 0
	v_mul_f32_e32 v46, v43, v43
	v_mul_f32_e32 v47, v45, v45
	v_fmac_f32_e32 v30, v26, v26
	v_fmac_f32_e32 v31, v28, v28
	v_and_b32_e32 v32, 64, v170
	v_add_f32_e32 v78, v78, v79
	v_add_f32_e32 v62, v62, v63
	v_fmac_f32_e32 v46, v42, v42
	v_fmac_f32_e32 v47, v44, v44
	v_add_f32_e32 v30, v30, v31
	v_xor_b32_e32 v31, 16, v170
	v_add_u32_e32 v32, 64, v32
	v_add_f32_e32 v62, v78, v62
	v_add_f32_e32 v46, v46, v47
	v_cmp_lt_i32_e64 s[0:1], v31, v32
	v_add_f32_e32 v46, v62, v46
	v_add_f32_e32 v30, v46, v30
	v_cndmask_b32_e64 v31, v170, v31, s[0:1]
	v_lshlrev_b32_e32 v31, 2, v31
	ds_bpermute_b32 v31, v31, v30
	s_waitcnt lgkmcnt(0)
	v_add_f32_e32 v30, v30, v31
	v_xor_b32_e32 v31, 32, v170
	v_cmp_lt_i32_e64 s[0:1], v31, v32
	s_nop 1
	v_cndmask_b32_e64 v31, v170, v31, s[0:1]
	v_lshlrev_b32_e32 v31, 2, v31
	ds_bpermute_b32 v31, v31, v30
	s_and_saveexec_b64 s[0:1], s[20:21]
	s_cbranch_execz .LBB0_750
	s_waitcnt lgkmcnt(0)
	v_add_f32_e32 v30, v30, v31
	ds_write_b32 v171, v30
	s_branch .LBB0_750
.Ltramp_fwd:
	s_branch .Lp0_entry
.Ltramp_back:
	s_branch .Ltail_return
.LBB0_757:
	v_readlane_b32 s88, v228, 6
	v_readlane_b32 s58, v228, 12
	v_readlane_b32 s94, v228, 16
	v_readlane_b32 s89, v228, 7
	v_readlane_b32 s59, v228, 13
	v_readlane_b32 s56, v228, 8
	v_readlane_b32 s57, v228, 9
	v_readlane_b32 s95, v228, 17

.LBB0_1343:
	s_waitcnt vmcnt(0)
	s_barrier
	s_cmp_lg_u32 s88, 0x100
	s_cbranch_scc1 .Ltail_skip
	s_cmp_lt_u32 s94, 0x80
	s_cbranch_scc1 .Ltail_skip
	v_writelane_b32 v228, s4, 18
	v_writelane_b32 v228, s5, 19
	v_readlane_b32 s0, v228, 12
	v_readlane_b32 s1, v228, 13
	s_sub_u32 s0, s0, 0xb0
	s_subb_u32 s1, s1, 0
	s_load_dwordx16 s[60:75], s[0:1], 0x0
	s_load_dwordx4 s[76:79], s[0:1], 0x80
	s_mov_b32 s101, 1
	s_movk_i32 s99, 0x44ff
	s_movk_i32 s100, 0x3a00
	s_waitcnt lgkmcnt(0)
	s_branch .Ltramp_fwd
.Ltail_return:
	v_readlane_b32 s4, v228, 18
	v_readlane_b32 s5, v228, 19
	s_add_u32 s62, s84, 0xb000000
	s_addc_u32 s63, s85, 0
	s_add_u32 s64, s84, 0xf800000
	s_addc_u32 s65, s85, 0
	s_add_u32 s70, s84, 0x13800000
	s_addc_u32 s71, s85, 0
	s_mov_b32 s101, 0
.Ltail_skip:
.LBB0_1344:
	s_cmp_gt_i32 s87, 11
	s_cselect_b64 s[0:1], -1, 0
	s_and_b64 s[2:3], s[4:5], s[0:1]
	s_andn2_b64 vcc, exec, s[2:3]
	s_cbranch_vccnz .LBB0_1412
	s_cmp_gt_i32 s86, -1
	s_mov_b64 s[4:5], -1
	s_cbranch_scc0 .LBB0_1399
	s_waitcnt vmcnt(0)
	s_waitcnt vmcnt(0) lgkmcnt(0)
	s_barrier
	s_mov_b64 s[4:5], exec
	v_readlane_b32 s2, v228, 4
	v_readlane_b32 s3, v228, 5
	s_and_b64 s[2:3], s[4:5], s[2:3]
	s_mov_b64 exec, s[2:3]
	s_cbranch_execz .LBB0_1398
	s_add_i32 s2, 0, 0x23fc0
	v_mov_b32_e32 v1, s2
	s_waitcnt vmcnt(0) expcnt(0) lgkmcnt(0)
	ds_read_b32 v3, v1
	s_add_i32 s2, 0, 0x23fc4
	v_mov_b32_e32 v1, s2
	ds_read_b32 v1, v1
	s_waitcnt lgkmcnt(1)
	v_cmp_ne_u32_e32 vcc, 0, v3
	s_cbranch_vccnz .LBB0_1362
	s_add_u32 s6, s84, 0x30200
	s_addc_u32 s7, s85, 0
	s_add_u32 s8, s84, 0x30400
	s_addc_u32 s9, s85, 0
	s_add_u32 s10, s84, 0x30500
	s_addc_u32 s11, s85, 0
	s_add_u32 s12, s84, 0x30600
	s_addc_u32 s13, s85, 0
	s_add_u32 s14, s84, 0x30700
	s_addc_u32 s15, s85, 0
	s_add_u32 s16, s84, 0x30800
	s_addc_u32 s17, s85, 0
	s_add_u32 s18, s84, 0x30900
	s_addc_u32 s19, s85, 0
	s_add_u32 s20, s84, 0x30a00
	s_addc_u32 s21, s85, 0
	s_add_u32 s22, s84, 0x30b00
	s_addc_u32 s23, s85, 0
	s_add_u32 s24, s84, 0x30c00
	s_addc_u32 s25, s85, 0
	s_add_u32 s26, s84, 0x30d00
	s_addc_u32 s27, s85, 0
	s_add_u32 s28, s84, 0x30e00
	s_addc_u32 s29, s85, 0
	s_add_u32 s30, s84, 0x30f00
	s_addc_u32 s31, s85, 0
	s_add_u32 s34, s84, 0x31000
	s_addc_u32 s35, s85, 0
	s_add_u32 s36, s84, 0x31100
	s_addc_u32 s37, s85, 0
	s_add_u32 s38, s84, 0x31200
	v_readlane_b32 s2, v228, 0
	s_addc_u32 s39, s85, 0
	s_mul_i32 s2, s89, s2
	s_add_u32 s40, s84, 0x31300
	s_mul_i32 s2, s2, s88
	s_addc_u32 s41, s85, 0
	s_mov_b32 s3, 1
	v_mov_b32_e32 v17, 0
	s_branch .LBB0_1350

	.amdhsa_kernel _Z10fwd_kernel4Args
		.amdhsa_group_segment_fixed_size 0
		.amdhsa_private_segment_fixed_size 0
		.amdhsa_kernarg_size 432
		.amdhsa_user_sgpr_count 2
		.amdhsa_user_sgpr_dispatch_ptr 0
		.amdhsa_user_sgpr_queue_ptr 0
		.amdhsa_user_sgpr_kernarg_segment_ptr 1
		.amdhsa_user_sgpr_dispatch_id 0
		.amdhsa_user_sgpr_kernarg_preload_length 0
		.amdhsa_user_sgpr_kernarg_preload_offset 0
		.amdhsa_user_sgpr_private_segment_size 0
		.amdhsa_uses_dynamic_stack 0
		.amdhsa_enable_private_segment 0
		.amdhsa_system_sgpr_workgroup_id_x 1
		.amdhsa_system_sgpr_workgroup_id_y 0
		.amdhsa_system_sgpr_workgroup_id_z 0
		.amdhsa_system_sgpr_workgroup_info 0
		.amdhsa_system_vgpr_workitem_id 2
		.amdhsa_next_free_vgpr 256
		.amdhsa_next_free_sgpr 102
		.amdhsa_accum_offset 256
		.amdhsa_reserve_vcc 1
		.amdhsa_float_round_mode_32 0
		.amdhsa_float_round_mode_16_64 0
		.amdhsa_float_denorm_mode_32 3
		.amdhsa_float_denorm_mode_16_64 3
		.amdhsa_dx10_clamp 1
		.amdhsa_ieee_mode 1
		.amdhsa_fp16_overflow 0
		.amdhsa_tg_split 0
		.amdhsa_exception_fp_ieee_invalid_op 0
		.amdhsa_exception_fp_denorm_src 0
		.amdhsa_exception_fp_ieee_div_zero 0
		.amdhsa_exception_fp_ieee_overflow 0
		.amdhsa_exception_fp_ieee_underflow 0
		.amdhsa_exception_fp_ieee_inexact 0
		.amdhsa_exception_int_div_zero 0
	.end_amdhsa_kernel
